# stack4: stack3 + last P4 ticket holder skips the exhausted-queue pop + P4 item store drain overlaps next pop (one barrier fewer per item)
# speedup vs baseline: 1.0205x; 1.0048x over previous
.LBB0_625:
	s_cbranch_execz .LBB0_592
	s_add_u32 s4, s66, 0xbf00
	s_addc_u32 s5, s67, 0
	s_add_u32 s25, s66, 0xb00000
	s_addc_u32 s27, s67, 0
	s_add_u32 s2, s66, 0x12000000
	s_addc_u32 s3, s67, 0
	s_add_u32 s0, s66, 0xec40080
	s_addc_u32 s1, s67, 0
	s_add_u32 s24, s66, 0xb00100
	s_addc_u32 s26, s67, 0
	s_add_i32 s29, 0, 0x20174
	v_mov_b32_e32 v129, 0
	s_movk_i32 s28, 0x100
	v_mov_b32_e32 v140, s29
	s_mov_b32 s48, 0x1fffe0
	s_mov_b64 s[6:7], 0x40000
	s_mov_b64 s[8:9], 0x80
	s_mov_b32 s49, 0x40000
	s_mov_b64 s[10:11], 0x48000
	s_mov_b32 s50, 0x48000
	s_mov_b64 s[12:13], 0x50000
	s_mov_b32 s51, 0x50000
	s_mov_b64 s[14:15], 0x58000
	s_mov_b32 s52, 0x58000
	v_mov_b32_e32 v141, 1
	s_mov_b32 s100, 0
	s_branch .LBB0_628

.LBB0_628:
	s_and_b64 vcc, exec, s[72:73]
	s_barrier
	s_cbranch_vccnz .LBB0_650
	v_mbcnt_lo_u32_b32 v0, -1, 0
	v_mbcnt_hi_u32_b32 v0, -1, v0
	s_nop 0
	v_cmp_eq_u32_e32 vcc, 0, v0
	s_and_saveexec_b64 s[16:17], vcc
	s_cbranch_execz .LBB0_649
	s_cmpk_eq_u32 s100, 0xff
	s_cbranch_scc1 .Lp4_drained
	s_mov_b64 s[22:23], exec
	v_mbcnt_lo_u32_b32 v0, s22, 0
	v_mbcnt_hi_u32_b32 v0, s23, v0
	v_cmp_eq_u32_e32 vcc, 0, v0
	s_and_saveexec_b64 s[18:19], vcc
	s_cbranch_execz .LBB0_632
	s_bcnt1_i32_b64 s22, s[22:23]
	v_mov_b32_e32 v1, s22
	global_atomic_add v1, v129, v1, s[4:5] sc0
	buffer_inv sc1
.LBB0_632:
	s_or_b64 exec, exec, s[18:19]
	s_waitcnt vmcnt(0)
	v_readfirstlane_b32 s18, v1
	v_mov_b32_e32 v2, 0
	s_nop 0
	v_add_u32_e32 v0, s18, v0
	v_cmp_gt_u32_e32 vcc, s28, v0
	v_readfirstlane_b32 s100, v0
	s_and_saveexec_b64 s[18:19], vcc
	s_cbranch_execz .LBB0_648
	v_lshlrev_b32_e32 v128, 2, v0
	v_lshl_add_u64 v[0:1], v[128:129], 2, s[66:67]
	global_load_dword v2, v[0:1], off sc1
	s_waitcnt vmcnt(0)
	v_cmp_eq_u32_e32 vcc, 0, v2
	s_and_saveexec_b64 s[22:23], vcc
	s_cbranch_execz .LBB0_647
	s_mov_b32 s53, 1
	s_mov_b64 s[34:35], 0
	s_branch .LBB0_636

.Lp4_store_slot:
	v_mov_b32_e32 v0, s29
	ds_write_b32 v0, v2
	s_branch .LBB0_649
.Lp4_drained:
	v_mov_b32_e32 v2, 0
	s_branch .Lp4_store_slot
